# 288-unit GEMM phases staggered: workgroups with split slot >= 16 run their split-K slice first, whole unit second, so one half's epilogue/exchange memory bursts overlap the other half's K-loops; on to
# speedup vs baseline: 1.0089x; 1.0029x over previous
.LBB0_770:
	s_andn2_b64 vcc, exec, s[6:7]
	s_cbranch_vccnz .LBB0_1633
	s_ashr_i32 s1, s16, 8
	s_ashr_i32 s0, s16, 6
	v_and_b32_e32 v239, 15, v2
	s_lshl_b32 s7, s1, 6
	v_and_b32_e32 v5, 48, v2
	v_lshlrev_b32_e32 v6, 2, v2
	s_and_b32 s6, s0, 3
	v_writelane_b32 v255, s7, 18
	s_lshl_b32 s7, s1, 13
	v_lshl_or_b32 v5, v239, 6, v5
	v_and_b32_e32 v6, 32, v6
	v_bitop3_b32 v7, v5, s7, v6 bitop3:0xde
	s_lshl_b32 s7, s6, 12
	v_bitop3_b32 v252, v5, s7, v6 bitop3:0xde
	v_ashrrev_i32_e32 v6, 31, v2
	v_lshrrev_b32_e32 v6, 26, v6
	v_and_b32_e32 v4, 63, v2
	v_bfe_u32 v241, v2, 4, 2
	v_lshlrev_b32_e32 v5, 4, v2
	v_add_u32_e32 v6, v2, v6
	v_bfe_i32 v2, v2, 27, 1
	v_lshrrev_b32_e32 v2, 22, v2
	v_add_u32_e32 v2, v5, v2
	v_and_b32_e32 v2, 0xfffffc00, v2
	v_sub_u32_e32 v2, v5, v2
	v_lshrrev_b32_e32 v8, 4, v2
	v_bitop3_b32 v2, v8, v2, 32 bitop3:0x6c
	s_lshl_b32 s5, s0, 10
	s_lshl_b32 s70, s6, 5
	v_ashrrev_i32_e32 v9, 31, v2
	s_cmp_eq_u32 s1, 1
	v_ashrrev_i32_e32 v6, 6, v6
	v_lshrrev_b32_e32 v9, 26, v9
	s_cselect_b64 s[8:9], -1, 0
	s_cmp_lt_i32 s0, 4
	v_lshlrev_b32_e32 v8, 3, v6
	v_add_u32_e32 v9, v2, v9
	s_cselect_b64 s[54:55], -1, 0
	s_cmp_lt_i32 s0, 2
	v_and_b32_e32 v8, -16, v8
	v_ashrrev_i32_e32 v10, 6, v9
	s_cselect_b64 s[38:39], -1, 0
	s_cmp_eq_u32 s0, 2
	v_add_u32_e32 v235, v10, v8
	v_and_b32_e32 v8, 0xc0, v9
	s_cselect_b64 s[22:23], -1, 0
	s_lshl_b32 s30, s0, 8
	v_sub_u32_e32 v2, v2, v8
	v_mov_b32_e32 v11, 1
	v_writelane_b32 v255, s8, 19
	s_cmpk_lt_u32 s16, 0x100
	v_lshlrev_b32_e32 v6, 5, v6
	v_ashrrev_i16_sdwa v2, v11, sext(v2) dst_sel:DWORD dst_unused:UNUSED_PAD src0_sel:DWORD src1_sel:BYTE_0
	v_writelane_b32 v255, s9, 20
	s_cselect_b64 s[0:1], -1, 0
	v_and_b32_e32 v6, 32, v6
	v_bfe_i32 v2, v2, 0, 16
	v_writelane_b32 v255, s0, 21
	s_cmp_eq_u32 s6, 0
	v_add_lshl_u32 v192, v6, v2, 1
	v_add_u32_e32 v2, 0x2000, v5
	v_writelane_b32 v255, s1, 22
	s_cselect_b64 s[0:1], -1, 0
	v_ashrrev_i32_e32 v5, 31, v2
	v_writelane_b32 v255, s0, 23
	v_lshrrev_b32_e32 v5, 22, v5
	v_add_u32_e32 v5, v2, v5
	v_writelane_b32 v255, s1, 24
	v_ashrrev_i32_e32 v5, 10, v5
	s_mul_i32 s0, s14, s15
	v_readlane_b32 s6, v255, 13
	v_mul_i32_i24_e32 v6, 0x400, v5
	s_cmp_le_i32 s0, s6
	v_sub_u32_e32 v2, v2, v6
	s_cselect_b32 s0, s15, 1
	s_cmp_gt_i32 s14, 0
	v_lshlrev_b32_e32 v8, 1, v235
	v_lshrrev_b32_e32 v9, 2, v235
	v_and_b32_e32 v10, 3, v10
	s_movk_i32 s1, 0xffe0
	v_lshrrev_b32_e32 v6, 4, v2
	s_cselect_b64 s[6:7], -1, 0
	v_and_b32_e32 v8, 24, v8
	v_and_b32_e32 v9, 4, v9
	v_and_or_b32 v10, v235, s1, v10
	v_bitop3_b32 v2, v6, v2, 32 bitop3:0x6c
	v_writelane_b32 v255, s6, 25
	v_or3_b32 v238, v10, v9, v8
	v_ashrrev_i32_e32 v8, 31, v2
	v_writelane_b32 v255, s7, 26
	v_lshrrev_b32_e32 v8, 26, v8
	v_writelane_b32 v255, s0, 27
	s_mul_i32 s0, s0, s14
	v_lshlrev_b32_e32 v6, 3, v5
	v_add_u32_e32 v8, v2, v8
	s_cmp_lt_i32 s57, s0
	v_and_b32_e32 v6, -16, v6
	v_ashrrev_i32_e32 v9, 6, v8
	s_cselect_b64 s[6:7], -1, 0
	s_abs_i32 s0, s14
	v_add_u32_e32 v240, v9, v6
	v_and_b32_e32 v6, 0xc0, v8
	v_cvt_f32_u32_e32 v8, s0
	v_sub_u32_e32 v2, v2, v6
	v_lshlrev_b32_e32 v5, 5, v5
	v_ashrrev_i16_sdwa v2, v11, sext(v2) dst_sel:DWORD dst_unused:UNUSED_PAD src0_sel:DWORD src1_sel:BYTE_0
	v_rcp_iflag_f32_e32 v8, v8
	v_and_b32_e32 v5, 32, v5
	v_bfe_i32 v2, v2, 0, 16
	v_add_lshl_u32 v194, v5, v2, 1
	v_mul_f32_e32 v2, 0x4f7ffffe, v8
	v_cvt_u32_f32_e32 v2, v2
	v_writelane_b32 v255, s6, 28
	v_readlane_b32 s8, v253, 22
	v_and_b32_e32 v9, 3, v9
	v_writelane_b32 v255, s7, 29
	s_sub_i32 s6, 0, s0
	v_readfirstlane_b32 s7, v2
	s_mul_i32 s6, s6, s7
	s_mul_hi_u32 s6, s7, s6
	s_add_i32 s7, s7, s6
	s_mul_hi_u32 s6, s8, s7
	s_mul_i32 s7, s6, s0
	v_and_or_b32 v9, v240, s1, v9
	s_ashr_i32 s1, s14, 31
	s_sub_i32 s7, s8, s7
	s_xor_b32 s1, s62, s1
	s_add_i32 s8, s6, 1
	s_sub_i32 s9, s7, s0
	s_cmp_ge_u32 s7, s0
	s_cselect_b32 s6, s8, s6
	s_cselect_b32 s7, s9, s7
	s_add_i32 s8, s6, 1
	s_cmp_ge_u32 s7, s0
	s_cselect_b32 s0, s8, s6
	s_xor_b32 s0, s0, s1
	s_sub_i32 s1, s0, s1
	s_mul_i32 s0, s1, s14
	s_sub_i32 s0, s57, s0
	v_writelane_b32 v255, s0, 30
	s_add_i32 s74, s0, s2
	s_lshl_b32 s0, s1, 2
	s_lshl_b32 s0, 15, s0
	v_writelane_b32 v255, s0, 31
	s_lshl_b32 s0, s1, 1
	s_lshl_b32 s0, 3, s0
	s_cmp_eq_u32 s1, 1
	v_writelane_b32 v255, s0, 32
	s_cselect_b32 s0, 56, 0xc0
	s_cmp_lg_u32 s1, 0
	s_cselect_b32 s0, s0, 7
	v_lshlrev_b32_e32 v6, 1, v240
	v_lshrrev_b32_e32 v10, 2, v240
	v_writelane_b32 v255, s0, 33
	v_lshlrev_b32_e32 v4, 2, v4
	v_and_b32_e32 v6, 24, v6
	v_and_b32_e32 v10, 4, v10
	v_writelane_b32 v255, s1, 34
	s_lshl_b32 s0, 1, s1
	v_mov_b32_e32 v243, v245
	s_mov_b32 s82, 0
	v_mov_b32_e32 v193, 1
	v_or3_b32 v242, v9, v10, v6
	v_writelane_b32 v255, s0, 35
	v_lshlrev_b32_e32 v221, 2, v4
	v_add_u32_e32 v229, 0, v7
	v_readlane_b32 s0, v255, 14
	s_cmp_lg_u32 s0, 1
	s_cbranch_scc1 .Lstag_done
	v_readlane_b32 s0, v255, 27
	s_cmp_lg_u32 s0, 8
	s_cbranch_scc1 .Lstag_done
	s_cmp_lg_u32 s14, 32
	s_cbranch_scc1 .Lstag_done
	v_readlane_b32 s0, v255, 28
	s_cmp_eq_u32 s0, 0
	s_cbranch_scc1 .Lstag_done
	v_readlane_b32 s2, v255, 30
	s_cmp_lt_u32 s2, 16
	s_cbranch_scc1 .Lstag_done
	s_add_i32 s0, s2, 0x100
	s_and_b32 s33, s0, 7
	s_lshr_b32 s0, s0, 3
	s_mul_i32 s33, s33, 36
	s_add_i32 s0, s0, s33
	s_lshr_b32 s80, s0, 6
	s_lshl_b32 s80, s80, 3
	s_and_b32 s0, s0, 63
	s_cmp_eq_u32 s80, 32
	s_cselect_b32 s94, 3, 7
	s_cselect_b32 s96, 2, 3
	s_and_b32 s94, s0, s94
	s_add_i32 s4, s80, s94
	s_lshr_b32 s3, s0, s96
	s_mov_b32 s75, 0
	v_readlane_b32 s67, v255, 34
	s_mov_b32 s85, 8
	v_readlane_b32 s84, v255, 35
	v_writelane_b32 v255, s2, 17
	s_mov_b32 s0, 0
	s_nop 0
	v_writelane_b32 v255, s0, 28
	v_writelane_b32 v255, s0, 29
	s_mov_b32 s82, -1
.Lstag_done:
.LBB0_772:
	s_lshl_b32 s0, s75, 6
	s_add_i32 s0, s0, 0
	s_add_i32 s0, s0, 0x21400
	v_mov_b32_e32 v2, s0
	s_waitcnt lgkmcnt(0)
	ds_read2_b32 v[4:5], v2 offset0:9 offset1:10
	ds_read2_b32 v[6:7], v2 offset0:11 offset1:12
	ds_read2_b32 v[8:9], v2 offset0:13 offset1:14
	ds_read_b32 v2, v2 offset:60
	s_abs_i32 s0, s85
	s_waitcnt lgkmcnt(0)
	v_readfirstlane_b32 s88, v5
	v_cvt_f32_u32_e32 v5, s0
	s_sub_i32 s8, 0, s0
	s_waitcnt lgkmcnt(0)
	v_readfirstlane_b32 s12, v2
	v_readfirstlane_b32 s1, v4
	v_rcp_iflag_f32_e32 v2, v5
	s_ashr_i32 s1, s1, 1
	s_abs_i32 s7, s1
	s_xor_b32 s6, s1, s85
	v_mul_f32_e32 v2, 0x4f7ffffe, v2
	v_cvt_u32_f32_e32 v2, v2
	s_ashr_i32 s6, s6, 31
	v_readfirstlane_b32 s10, v8
	v_readfirstlane_b32 s11, v7
	v_readfirstlane_b32 s9, v2
	s_mul_i32 s8, s8, s9
	s_mul_hi_u32 s8, s9, s8
	s_add_i32 s9, s9, s8
	s_mul_hi_u32 s8, s7, s9
	s_mul_i32 s9, s8, s0
	s_sub_i32 s7, s7, s9
	s_add_i32 s9, s8, 1
	s_sub_i32 s14, s7, s0
	s_cmp_ge_u32 s7, s0
	s_cselect_b32 s8, s9, s8
	s_cselect_b32 s7, s14, s7
	s_add_i32 s9, s8, 1
	s_cmp_ge_u32 s7, s0
	s_cselect_b32 s0, s9, s8
	s_xor_b32 s0, s0, s6
	s_sub_i32 s6, s0, s6
	s_mul_i32 s0, s6, s85
	s_sub_i32 s7, s1, s0
	s_min_i32 s0, s67, s7
	s_mul_i32 s1, s6, s67
	s_ashr_i32 s8, s4, 31
	s_add_i32 s0, s0, s1
	s_mul_i32 s8, s8, s88
	s_mul_hi_u32 s9, s4, s88
	s_lshl_b32 s0, s0, 1
	s_mov_b32 s1, s41
	s_add_i32 s9, s9, s8
	s_mul_i32 s8, s4, s88
	s_lshl_b64 s[0:1], s[0:1], 7
	s_lshl_b64 s[8:9], s[8:9], 8
	s_add_u32 s8, 0, s8
	s_addc_u32 s9, s10, s9
	s_add_u32 s8, s8, s11
	s_addc_u32 s9, s9, 0
	s_add_u32 s90, s8, s0
	v_readfirstlane_b32 s86, v6
	s_addc_u32 s91, s9, s1
	s_ashr_i32 s8, s3, 31
	s_mul_i32 s8, s8, s86
	s_mul_hi_u32 s9, s3, s86
	s_add_i32 s9, s9, s8
	s_mul_i32 s8, s3, s86
	s_lshl_b64 s[8:9], s[8:9], 8
	s_add_u32 s8, 0, s8
	v_readfirstlane_b32 s13, v9
	s_addc_u32 s9, s12, s9
	s_add_u32 s8, s8, s13
	s_addc_u32 s9, s9, 0
	s_add_u32 s52, s8, s0
	s_addc_u32 s53, s9, s1
	s_add_i32 s78, s5, 0
	s_mov_b32 s89, s41
	s_mov_b32 s87, s41
	v_mad_u64_u32 v[196:197], s[0:1], s88, v235, v[192:193]
	v_mad_u64_u32 v[198:199], s[0:1], s86, v238, v[192:193]
	v_mad_u64_u32 v[200:201], s[0:1], s88, v240, v[194:195]
	v_mad_u64_u32 v[202:203], s[0:1], s86, v242, v[194:195]
	s_add_i32 m0, s78, 0x10000
	s_lshl_b64 s[8:9], s[88:89], 7
	global_load_lds_dwordx4 v198, s[52:53]
	s_add_i32 m0, s78, 0x12000
	s_lshl_b64 s[0:1], s[86:87], 7
	s_add_u32 s0, s52, s0
	global_load_lds_dwordx4 v202, s[52:53]
	s_addc_u32 s1, s53, s1
	s_add_i32 m0, s78, 0x14000
	s_add_i32 s87, s78, 0x2000
	global_load_lds_dwordx4 v198, s[0:1]
	s_add_i32 m0, s78, 0x16000
	s_add_u32 s8, s90, s8
	global_load_lds_dwordx4 v202, s[0:1]
	s_mov_b32 m0, s78
	s_addc_u32 s9, s91, s9
	global_load_lds_dwordx4 v196, s[90:91]
	s_mov_b32 m0, s87
	s_add_i32 s79, s78, 0x4000
	global_load_lds_dwordx4 v200, s[90:91]
	s_mov_b32 m0, s79
	s_add_i32 s34, s78, 0x6000
	global_load_lds_dwordx4 v196, s[8:9]
	s_mov_b32 m0, s34
	s_nop 0
	global_load_lds_dwordx4 v200, s[8:9]
	v_readlane_b32 s8, v255, 19
	v_readlane_b32 s9, v255, 20
	s_andn2_b64 vcc, exec, s[8:9]
	s_nop 0
	v_cndmask_b32_e64 v2, 0, 1, s[8:9]
	v_cmp_ne_u32_e64 s[10:11], 1, v2
	s_nop 1
	v_writelane_b32 v255, s10, 36
	s_nop 1
	v_writelane_b32 v255, s11, 37
	s_cbranch_vccnz .LBB0_774
	s_barrier
